# speedup vs baseline: 1.0109x; 1.0109x over previous
; #define GAS __attribute__((address_space(1)))
; __device__ __forceinline__ unsigned pk2(float lo, float hi) { unsigned r; asm("s_nop 1\n\tv_cvt_pk_bf16_f32 %0, %1, %2" : "=v"(r) : "v"(lo), "v"(hi)); return r; }
; __device__ __forceinline__ unsigned f2bf(float f) { return pk2(f, f) & 0xffffu; }
; __device__ __forceinline__ float sigmoidf_(float v) { return __builtin_amdgcn_rcpf(1.f + __builtin_amdgcn_exp2f(-LOG2E * v)); }
; __device__ __forceinline__ void phase_up(int pass) {
;     ...
;     if (L < NT_) { tile_coords(L, nN, pm, pn); gemm_prefetch<DM>(A, Wgu, pm * 256, pn * 256); load_rr(ssq, pm * 256, par ^ 1); }
;     EPI_IDS
;     const float* rr = (const float*)(smem_raw + LDS_RR) + par * 256;
;     GAS char* tb = (GAS char*)act + ((size_t)brow * FFP + (bcol >> 1)) * 2;
;     const unsigned off0 = (unsigned)((wr * 64 + fq * 4) * FFP + wc * 16 + fr) * 2u;
; #pragma unroll
;     for (int ai = 0; ai < 2; ++ai)
; #pragma unroll
;       for (int m = 0; m < 4; ++m)
; #pragma unroll
;         for (int j = 0; j < 4; ++j) {
;           const int rowl = ai * 128 + wr * 64 + m * 16 + fq * 4 + j;
;           const float r = rr[rowl];
; #pragma unroll
;           for (int bj = 0; bj < 2; ++bj) {
;             const float g = acc[ai][bj][m][0][j] * r, u = acc[ai][bj][m][1][j] * r;
;             const float v = g * sigmoidf_(g) * u;
;             *(GAS unsigned short*)(tb + (off0 + (unsigned)(((ai * 128 + m * 16 + j) * FFP + bj * 64) * 2))) = (unsigned short)f2bf(v);
;           }
;         }
;     par ^= 1;
.LBB0_85:
	v_ashrrev_i32_e32 v218, 2, v170
	v_and_b32_e32 v218, 0xffffffc0, v218
	v_lshrrev_b32_e32 v174, 2, v170
	v_and_b32_e32 v175, 12, v174
	v_or_b32_e32 v176, v218, v175
	v_and_b32_e32 v174, 48, v174
	v_and_b32_e32 v177, 15, v170
	v_mul_u32_u24_e32 v210, 0xb40, v176
	v_add3_u32 v210, v210, v174, v177
	v_lshlrev_b32_e32 v210, 1, v210
	v_add_u32_e32 v211, 0x1680, v210
	v_add_u32_e32 v212, 0x2d00, v210
	v_add_u32_e32 v213, 0x4380, v210
	s_lshl_b32 s18, s37, 10
	s_add_i32 s18, s18, 0x20100
	v_lshl_add_u32 v218, v176, 2, s18
	ds_read_b128 v[178:181], v218
	ds_read_b128 v[182:185], v218 offset:64
	ds_read_b128 v[186:189], v218 offset:128
	ds_read_b128 v[190:193], v218 offset:192
	ds_read_b128 v[194:197], v218 offset:512
	ds_read_b128 v[198:201], v218 offset:576
	ds_read_b128 v[202:205], v218 offset:640
	ds_read_b128 v[206:209], v218 offset:704
	v_mov_b32_e32 v214, 0xbfb8aa3b
	v_mov_b32_e32 v215, 0xbfb8aa3b
	v_mov_b32_e32 v216, 1.0
	v_mov_b32_e32 v217, 1.0
	s_lshl_b32 s19, s41, 7
	s_mul_hi_i32 s17, s16, 0xb40
	s_mulk_i32 s16, 0xb40
	s_ashr_i32 s20, s19, 31
	s_add_u32 s16, s16, s19
	s_addc_u32 s17, s17, s20
	s_lshl_b64 s[16:17], s[16:17], 1
	s_add_u32 s16, s35, s16
	s_addc_u32 s17, s36, s17
	s_waitcnt lgkmcnt(0)
	v_pk_mul_f32 v[118:119], v[118:119], v[178:179]
	v_pk_mul_f32 v[120:121], v[120:121], v[180:181]
	v_pk_mul_f32 v[174:175], v[214:215], v[118:119]
	v_pk_mul_f32 v[176:177], v[214:215], v[120:121]
	v_exp_f32_e32 v174, v174
	v_exp_f32_e32 v175, v175
	v_exp_f32_e32 v176, v176
	v_exp_f32_e32 v177, v177
	v_pk_mul_f32 v[114:115], v[114:115], v[178:179]
	v_pk_mul_f32 v[116:117], v[116:117], v[180:181]
	v_pk_add_f32 v[174:175], v[216:217], v[174:175]
	v_pk_add_f32 v[176:177], v[216:217], v[176:177]
	v_rcp_f32_e32 v174, v174
	v_rcp_f32_e32 v175, v175
	v_rcp_f32_e32 v176, v176
	v_rcp_f32_e32 v177, v177
	v_pk_mul_f32 v[118:119], v[118:119], v[174:175]
	v_pk_mul_f32 v[120:121], v[120:121], v[176:177]
	v_pk_mul_f32 v[114:115], v[114:115], v[118:119]
	v_pk_mul_f32 v[116:117], v[116:117], v[120:121]
	v_cvt_pk_bf16_f32 v114, v114, v115
	v_cvt_pk_bf16_f32 v115, v116, v117
	global_store_short v210, v114, s[16:17]
	global_store_short_d16_hi v211, v114, s[16:17]
	global_store_short v212, v115, s[16:17]
	global_store_short_d16_hi v213, v115, s[16:17]
	v_pk_mul_f32 v[126:127], v[126:127], v[178:179]
	v_pk_mul_f32 v[128:129], v[128:129], v[180:181]
	v_pk_mul_f32 v[174:175], v[214:215], v[126:127]
	v_pk_mul_f32 v[176:177], v[214:215], v[128:129]
	v_exp_f32_e32 v174, v174
	v_exp_f32_e32 v175, v175
	v_exp_f32_e32 v176, v176
	v_exp_f32_e32 v177, v177
	v_pk_mul_f32 v[122:123], v[122:123], v[178:179]
	v_pk_mul_f32 v[124:125], v[124:125], v[180:181]
	v_pk_add_f32 v[174:175], v[216:217], v[174:175]
	v_pk_add_f32 v[176:177], v[216:217], v[176:177]
	v_rcp_f32_e32 v174, v174
	v_rcp_f32_e32 v175, v175
	v_rcp_f32_e32 v176, v176
	v_rcp_f32_e32 v177, v177
	v_pk_mul_f32 v[126:127], v[126:127], v[174:175]
	v_pk_mul_f32 v[128:129], v[128:129], v[176:177]
	v_pk_mul_f32 v[122:123], v[122:123], v[126:127]
	v_pk_mul_f32 v[124:125], v[124:125], v[128:129]
	v_cvt_pk_bf16_f32 v122, v122, v123
	v_cvt_pk_bf16_f32 v123, v124, v125
	global_store_short v210, v122, s[16:17] offset:128
	global_store_short_d16_hi v211, v122, s[16:17] offset:128
	global_store_short v212, v123, s[16:17] offset:128
	global_store_short_d16_hi v213, v123, s[16:17] offset:128
	s_add_u32 s16, s16, 0x16800
	s_addc_u32 s17, s17, 0
	v_pk_mul_f32 v[102:103], v[102:103], v[182:183]
	v_pk_mul_f32 v[104:105], v[104:105], v[184:185]
	v_pk_mul_f32 v[174:175], v[214:215], v[102:103]
	v_pk_mul_f32 v[176:177], v[214:215], v[104:105]
	v_exp_f32_e32 v174, v174
	v_exp_f32_e32 v175, v175
	v_exp_f32_e32 v176, v176
	v_exp_f32_e32 v177, v177
	v_pk_mul_f32 v[98:99], v[98:99], v[182:183]
	v_pk_mul_f32 v[100:101], v[100:101], v[184:185]
	v_pk_add_f32 v[174:175], v[216:217], v[174:175]
	v_pk_add_f32 v[176:177], v[216:217], v[176:177]
	v_rcp_f32_e32 v174, v174
	v_rcp_f32_e32 v175, v175
	v_rcp_f32_e32 v176, v176
	v_rcp_f32_e32 v177, v177
	v_pk_mul_f32 v[102:103], v[102:103], v[174:175]
	v_pk_mul_f32 v[104:105], v[104:105], v[176:177]
	v_pk_mul_f32 v[98:99], v[98:99], v[102:103]
	v_pk_mul_f32 v[100:101], v[100:101], v[104:105]
	v_cvt_pk_bf16_f32 v98, v98, v99
	v_cvt_pk_bf16_f32 v99, v100, v101
	global_store_short v210, v98, s[16:17]
	global_store_short_d16_hi v211, v98, s[16:17]
	global_store_short v212, v99, s[16:17]
	global_store_short_d16_hi v213, v99, s[16:17]
	v_pk_mul_f32 v[110:111], v[110:111], v[182:183]
	v_pk_mul_f32 v[112:113], v[112:113], v[184:185]
	v_pk_mul_f32 v[174:175], v[214:215], v[110:111]
	v_pk_mul_f32 v[176:177], v[214:215], v[112:113]
	v_exp_f32_e32 v174, v174
	v_exp_f32_e32 v175, v175
	v_exp_f32_e32 v176, v176
	v_exp_f32_e32 v177, v177
	v_pk_mul_f32 v[106:107], v[106:107], v[182:183]
	v_pk_mul_f32 v[108:109], v[108:109], v[184:185]
	v_pk_add_f32 v[174:175], v[216:217], v[174:175]
	v_pk_add_f32 v[176:177], v[216:217], v[176:177]
	v_rcp_f32_e32 v174, v174
	v_rcp_f32_e32 v175, v175
	v_rcp_f32_e32 v176, v176
	v_rcp_f32_e32 v177, v177
	v_pk_mul_f32 v[110:111], v[110:111], v[174:175]
	v_pk_mul_f32 v[112:113], v[112:113], v[176:177]
	v_pk_mul_f32 v[106:107], v[106:107], v[110:111]
	v_pk_mul_f32 v[108:109], v[108:109], v[112:113]
	v_cvt_pk_bf16_f32 v106, v106, v107
	v_cvt_pk_bf16_f32 v107, v108, v109
	global_store_short v210, v106, s[16:17] offset:128
	global_store_short_d16_hi v211, v106, s[16:17] offset:128
	global_store_short v212, v107, s[16:17] offset:128
	global_store_short_d16_hi v213, v107, s[16:17] offset:128
	s_add_u32 s16, s16, 0x16800
	s_addc_u32 s17, s17, 0
	v_pk_mul_f32 v[86:87], v[86:87], v[186:187]
; #define GAS __attribute__((address_space(1)))
; __device__ __forceinline__ unsigned pk2(float lo, float hi) { unsigned r; asm("s_nop 1\n\tv_cvt_pk_bf16_f32 %0, %1, %2" : "=v"(r) : "v"(lo), "v"(hi)); return r; }
; __device__ __forceinline__ unsigned f2bf(float f) { return pk2(f, f) & 0xffffu; }
; __device__ __forceinline__ float sigmoidf_(float v) { return __builtin_amdgcn_rcpf(1.f + __builtin_amdgcn_exp2f(-LOG2E * v)); }
; __device__ __forceinline__ void phase_up(int pass) {
;     ...
;     if (L < NT_) { tile_coords(L, nN, pm, pn); gemm_prefetch<DM>(A, Wgu, pm * 256, pn * 256); load_rr(ssq, pm * 256, par ^ 1); }
;     EPI_IDS
;     const float* rr = (const float*)(smem_raw + LDS_RR) + par * 256;
;     GAS char* tb = (GAS char*)act + ((size_t)brow * FFP + (bcol >> 1)) * 2;
;     const unsigned off0 = (unsigned)((wr * 64 + fq * 4) * FFP + wc * 16 + fr) * 2u;
; #pragma unroll
;     for (int ai = 0; ai < 2; ++ai)
; #pragma unroll
;       for (int m = 0; m < 4; ++m)
; #pragma unroll
;         for (int j = 0; j < 4; ++j) {
;           const int rowl = ai * 128 + wr * 64 + m * 16 + fq * 4 + j;
;           const float r = rr[rowl];
; #pragma unroll
;           for (int bj = 0; bj < 2; ++bj) {
;             const float g = acc[ai][bj][m][0][j] * r, u = acc[ai][bj][m][1][j] * r;
;             const float v = g * sigmoidf_(g) * u;
;             *(GAS unsigned short*)(tb + (off0 + (unsigned)(((ai * 128 + m * 16 + j) * FFP + bj * 64) * 2))) = (unsigned short)f2bf(v);
;           }
;         }
;     par ^= 1;
	v_pk_mul_f32 v[88:89], v[88:89], v[188:189]
	v_pk_mul_f32 v[174:175], v[214:215], v[86:87]
	v_pk_mul_f32 v[176:177], v[214:215], v[88:89]
	v_exp_f32_e32 v174, v174
	v_exp_f32_e32 v175, v175
	v_exp_f32_e32 v176, v176
	v_exp_f32_e32 v177, v177
	v_pk_mul_f32 v[82:83], v[82:83], v[186:187]
	v_pk_mul_f32 v[84:85], v[84:85], v[188:189]
	v_pk_add_f32 v[174:175], v[216:217], v[174:175]
	v_pk_add_f32 v[176:177], v[216:217], v[176:177]
	v_rcp_f32_e32 v174, v174
	v_rcp_f32_e32 v175, v175
	v_rcp_f32_e32 v176, v176
	v_rcp_f32_e32 v177, v177
	v_pk_mul_f32 v[86:87], v[86:87], v[174:175]
	v_pk_mul_f32 v[88:89], v[88:89], v[176:177]
	v_pk_mul_f32 v[82:83], v[82:83], v[86:87]
	v_pk_mul_f32 v[84:85], v[84:85], v[88:89]
	v_cvt_pk_bf16_f32 v82, v82, v83
	v_cvt_pk_bf16_f32 v83, v84, v85
	global_store_short v210, v82, s[16:17]
	global_store_short_d16_hi v211, v82, s[16:17]
	global_store_short v212, v83, s[16:17]
	global_store_short_d16_hi v213, v83, s[16:17]
	v_pk_mul_f32 v[94:95], v[94:95], v[186:187]
	v_pk_mul_f32 v[96:97], v[96:97], v[188:189]
	v_pk_mul_f32 v[174:175], v[214:215], v[94:95]
	v_pk_mul_f32 v[176:177], v[214:215], v[96:97]
	v_exp_f32_e32 v174, v174
	v_exp_f32_e32 v175, v175
	v_exp_f32_e32 v176, v176
	v_exp_f32_e32 v177, v177
	v_pk_mul_f32 v[90:91], v[90:91], v[186:187]
	v_pk_mul_f32 v[92:93], v[92:93], v[188:189]
	v_pk_add_f32 v[174:175], v[216:217], v[174:175]
	v_pk_add_f32 v[176:177], v[216:217], v[176:177]
	v_rcp_f32_e32 v174, v174
	v_rcp_f32_e32 v175, v175
	v_rcp_f32_e32 v176, v176
	v_rcp_f32_e32 v177, v177
	v_pk_mul_f32 v[94:95], v[94:95], v[174:175]
	v_pk_mul_f32 v[96:97], v[96:97], v[176:177]
	v_pk_mul_f32 v[90:91], v[90:91], v[94:95]
	v_pk_mul_f32 v[92:93], v[92:93], v[96:97]
	v_cvt_pk_bf16_f32 v90, v90, v91
	v_cvt_pk_bf16_f32 v91, v92, v93
	global_store_short v210, v90, s[16:17] offset:128
	global_store_short_d16_hi v211, v90, s[16:17] offset:128
	global_store_short v212, v91, s[16:17] offset:128
	global_store_short_d16_hi v213, v91, s[16:17] offset:128
	s_add_u32 s16, s16, 0x16800
	s_addc_u32 s17, s17, 0
	v_pk_mul_f32 v[70:71], v[70:71], v[190:191]
	v_pk_mul_f32 v[72:73], v[72:73], v[192:193]
	v_pk_mul_f32 v[174:175], v[214:215], v[70:71]
	v_pk_mul_f32 v[176:177], v[214:215], v[72:73]
	v_exp_f32_e32 v174, v174
	v_exp_f32_e32 v175, v175
	v_exp_f32_e32 v176, v176
	v_exp_f32_e32 v177, v177
	v_pk_mul_f32 v[66:67], v[66:67], v[190:191]
	v_pk_mul_f32 v[68:69], v[68:69], v[192:193]
	v_pk_add_f32 v[174:175], v[216:217], v[174:175]
	v_pk_add_f32 v[176:177], v[216:217], v[176:177]
	v_rcp_f32_e32 v174, v174
	v_rcp_f32_e32 v175, v175
	v_rcp_f32_e32 v176, v176
	v_rcp_f32_e32 v177, v177
	v_pk_mul_f32 v[70:71], v[70:71], v[174:175]
	v_pk_mul_f32 v[72:73], v[72:73], v[176:177]
	v_pk_mul_f32 v[66:67], v[66:67], v[70:71]
	v_pk_mul_f32 v[68:69], v[68:69], v[72:73]
	v_cvt_pk_bf16_f32 v66, v66, v67
	v_cvt_pk_bf16_f32 v67, v68, v69
	global_store_short v210, v66, s[16:17]
	global_store_short_d16_hi v211, v66, s[16:17]
	global_store_short v212, v67, s[16:17]
	global_store_short_d16_hi v213, v67, s[16:17]
	v_pk_mul_f32 v[78:79], v[78:79], v[190:191]
	v_pk_mul_f32 v[80:81], v[80:81], v[192:193]
	v_pk_mul_f32 v[174:175], v[214:215], v[78:79]
	v_pk_mul_f32 v[176:177], v[214:215], v[80:81]
	v_exp_f32_e32 v174, v174
	v_exp_f32_e32 v175, v175
	v_exp_f32_e32 v176, v176
	v_exp_f32_e32 v177, v177
	v_pk_mul_f32 v[74:75], v[74:75], v[190:191]
	v_pk_mul_f32 v[76:77], v[76:77], v[192:193]
	v_pk_add_f32 v[174:175], v[216:217], v[174:175]
	v_pk_add_f32 v[176:177], v[216:217], v[176:177]
	v_rcp_f32_e32 v174, v174
	v_rcp_f32_e32 v175, v175
	v_rcp_f32_e32 v176, v176
	v_rcp_f32_e32 v177, v177
	v_pk_mul_f32 v[78:79], v[78:79], v[174:175]
	v_pk_mul_f32 v[80:81], v[80:81], v[176:177]
	v_pk_mul_f32 v[74:75], v[74:75], v[78:79]
	v_pk_mul_f32 v[76:77], v[76:77], v[80:81]
	v_cvt_pk_bf16_f32 v74, v74, v75
	v_cvt_pk_bf16_f32 v75, v76, v77
	global_store_short v210, v74, s[16:17] offset:128
	global_store_short_d16_hi v211, v74, s[16:17] offset:128
	global_store_short v212, v75, s[16:17] offset:128
	global_store_short_d16_hi v213, v75, s[16:17] offset:128
	s_add_u32 s16, s16, 0x70800
	s_addc_u32 s17, s17, 0
	v_pk_mul_f32 v[54:55], v[54:55], v[194:195]
	v_pk_mul_f32 v[56:57], v[56:57], v[196:197]
	v_pk_mul_f32 v[174:175], v[214:215], v[54:55]
	v_pk_mul_f32 v[176:177], v[214:215], v[56:57]
	v_exp_f32_e32 v174, v174
	v_exp_f32_e32 v175, v175
	v_exp_f32_e32 v176, v176
	v_exp_f32_e32 v177, v177
	v_pk_mul_f32 v[50:51], v[50:51], v[194:195]
	v_pk_mul_f32 v[52:53], v[52:53], v[196:197]
	v_pk_add_f32 v[174:175], v[216:217], v[174:175]
	v_pk_add_f32 v[176:177], v[216:217], v[176:177]
	v_rcp_f32_e32 v174, v174
	v_rcp_f32_e32 v175, v175
	v_rcp_f32_e32 v176, v176
	v_rcp_f32_e32 v177, v177
	v_pk_mul_f32 v[54:55], v[54:55], v[174:175]
	v_pk_mul_f32 v[56:57], v[56:57], v[176:177]
	v_pk_mul_f32 v[50:51], v[50:51], v[54:55]
	v_pk_mul_f32 v[52:53], v[52:53], v[56:57]
	v_cvt_pk_bf16_f32 v50, v50, v51
	v_cvt_pk_bf16_f32 v51, v52, v53
	global_store_short v210, v50, s[16:17]
	global_store_short_d16_hi v211, v50, s[16:17]
	global_store_short v212, v51, s[16:17]
	global_store_short_d16_hi v213, v51, s[16:17]
	v_pk_mul_f32 v[62:63], v[62:63], v[194:195]
	v_pk_mul_f32 v[64:65], v[64:65], v[196:197]
	v_pk_mul_f32 v[174:175], v[214:215], v[62:63]
	v_pk_mul_f32 v[176:177], v[214:215], v[64:65]
	v_exp_f32_e32 v174, v174
	v_exp_f32_e32 v175, v175
	v_exp_f32_e32 v176, v176
	v_exp_f32_e32 v177, v177
	v_pk_mul_f32 v[58:59], v[58:59], v[194:195]
	v_pk_mul_f32 v[60:61], v[60:61], v[196:197]
	v_pk_add_f32 v[174:175], v[216:217], v[174:175]
	v_pk_add_f32 v[176:177], v[216:217], v[176:177]
	v_rcp_f32_e32 v174, v174
; #define GAS __attribute__((address_space(1)))
; __device__ __forceinline__ unsigned pk2(float lo, float hi) { unsigned r; asm("s_nop 1\n\tv_cvt_pk_bf16_f32 %0, %1, %2" : "=v"(r) : "v"(lo), "v"(hi)); return r; }
; __device__ __forceinline__ unsigned f2bf(float f) { return pk2(f, f) & 0xffffu; }
; __device__ __forceinline__ float sigmoidf_(float v) { return __builtin_amdgcn_rcpf(1.f + __builtin_amdgcn_exp2f(-LOG2E * v)); }
; __device__ __forceinline__ void phase_up(int pass) {
;     ...
;     if (L < NT_) { tile_coords(L, nN, pm, pn); gemm_prefetch<DM>(A, Wgu, pm * 256, pn * 256); load_rr(ssq, pm * 256, par ^ 1); }
;     EPI_IDS
;     const float* rr = (const float*)(smem_raw + LDS_RR) + par * 256;
;     GAS char* tb = (GAS char*)act + ((size_t)brow * FFP + (bcol >> 1)) * 2;
;     const unsigned off0 = (unsigned)((wr * 64 + fq * 4) * FFP + wc * 16 + fr) * 2u;
; #pragma unroll
;     for (int ai = 0; ai < 2; ++ai)
; #pragma unroll
;       for (int m = 0; m < 4; ++m)
; #pragma unroll
;         for (int j = 0; j < 4; ++j) {
;           const int rowl = ai * 128 + wr * 64 + m * 16 + fq * 4 + j;
;           const float r = rr[rowl];
; #pragma unroll
;           for (int bj = 0; bj < 2; ++bj) {
;             const float g = acc[ai][bj][m][0][j] * r, u = acc[ai][bj][m][1][j] * r;
;             const float v = g * sigmoidf_(g) * u;
;             *(GAS unsigned short*)(tb + (off0 + (unsigned)(((ai * 128 + m * 16 + j) * FFP + bj * 64) * 2))) = (unsigned short)f2bf(v);
;           }
;         }
;     par ^= 1;
	v_rcp_f32_e32 v175, v175
	v_rcp_f32_e32 v176, v176
	v_rcp_f32_e32 v177, v177
	v_pk_mul_f32 v[62:63], v[62:63], v[174:175]
	v_pk_mul_f32 v[64:65], v[64:65], v[176:177]
	v_pk_mul_f32 v[58:59], v[58:59], v[62:63]
	v_pk_mul_f32 v[60:61], v[60:61], v[64:65]
	v_cvt_pk_bf16_f32 v58, v58, v59
	v_cvt_pk_bf16_f32 v59, v60, v61
	global_store_short v210, v58, s[16:17] offset:128
	global_store_short_d16_hi v211, v58, s[16:17] offset:128
	global_store_short v212, v59, s[16:17] offset:128
	global_store_short_d16_hi v213, v59, s[16:17] offset:128
	s_add_u32 s16, s16, 0x16800
	s_addc_u32 s17, s17, 0
	v_pk_mul_f32 v[42:43], v[42:43], v[198:199]
	v_pk_mul_f32 v[44:45], v[44:45], v[200:201]
	v_pk_mul_f32 v[174:175], v[214:215], v[42:43]
	v_pk_mul_f32 v[176:177], v[214:215], v[44:45]
	v_exp_f32_e32 v174, v174
	v_exp_f32_e32 v175, v175
	v_exp_f32_e32 v176, v176
	v_exp_f32_e32 v177, v177
	v_pk_mul_f32 v[34:35], v[34:35], v[198:199]
	v_pk_mul_f32 v[36:37], v[36:37], v[200:201]
	v_pk_add_f32 v[174:175], v[216:217], v[174:175]
	v_pk_add_f32 v[176:177], v[216:217], v[176:177]
	v_rcp_f32_e32 v174, v174
	v_rcp_f32_e32 v175, v175
	v_rcp_f32_e32 v176, v176
	v_rcp_f32_e32 v177, v177
	v_pk_mul_f32 v[42:43], v[42:43], v[174:175]
	v_pk_mul_f32 v[44:45], v[44:45], v[176:177]
	v_pk_mul_f32 v[34:35], v[34:35], v[42:43]
	v_pk_mul_f32 v[36:37], v[36:37], v[44:45]
	v_cvt_pk_bf16_f32 v34, v34, v35
	v_cvt_pk_bf16_f32 v35, v36, v37
	global_store_short v210, v34, s[16:17]
	global_store_short_d16_hi v211, v34, s[16:17]
	global_store_short v212, v35, s[16:17]
	global_store_short_d16_hi v213, v35, s[16:17]
	v_pk_mul_f32 v[46:47], v[46:47], v[198:199]
	v_pk_mul_f32 v[48:49], v[48:49], v[200:201]
	v_pk_mul_f32 v[174:175], v[214:215], v[46:47]
	v_pk_mul_f32 v[176:177], v[214:215], v[48:49]
	v_exp_f32_e32 v174, v174
	v_exp_f32_e32 v175, v175
	v_exp_f32_e32 v176, v176
	v_exp_f32_e32 v177, v177
	v_pk_mul_f32 v[38:39], v[38:39], v[198:199]
	v_pk_mul_f32 v[40:41], v[40:41], v[200:201]
	v_pk_add_f32 v[174:175], v[216:217], v[174:175]
	v_pk_add_f32 v[176:177], v[216:217], v[176:177]
	v_rcp_f32_e32 v174, v174
	v_rcp_f32_e32 v175, v175
	v_rcp_f32_e32 v176, v176
	v_rcp_f32_e32 v177, v177
	v_pk_mul_f32 v[46:47], v[46:47], v[174:175]
	v_pk_mul_f32 v[48:49], v[48:49], v[176:177]
	v_pk_mul_f32 v[38:39], v[38:39], v[46:47]
	v_pk_mul_f32 v[40:41], v[40:41], v[48:49]
	v_cvt_pk_bf16_f32 v38, v38, v39
	v_cvt_pk_bf16_f32 v39, v40, v41
	global_store_short v210, v38, s[16:17] offset:128
	global_store_short_d16_hi v211, v38, s[16:17] offset:128
	global_store_short v212, v39, s[16:17] offset:128
	global_store_short_d16_hi v213, v39, s[16:17] offset:128
	s_add_u32 s16, s16, 0x16800
	s_addc_u32 s17, s17, 0
	v_pk_mul_f32 v[22:23], v[22:23], v[202:203]
	v_pk_mul_f32 v[24:25], v[24:25], v[204:205]
	v_pk_mul_f32 v[174:175], v[214:215], v[22:23]
	v_pk_mul_f32 v[176:177], v[214:215], v[24:25]
	v_exp_f32_e32 v174, v174
	v_exp_f32_e32 v175, v175
	v_exp_f32_e32 v176, v176
	v_exp_f32_e32 v177, v177
	v_pk_mul_f32 v[18:19], v[18:19], v[202:203]
	v_pk_mul_f32 v[20:21], v[20:21], v[204:205]
	v_pk_add_f32 v[174:175], v[216:217], v[174:175]
	v_pk_add_f32 v[176:177], v[216:217], v[176:177]
	v_rcp_f32_e32 v174, v174
	v_rcp_f32_e32 v175, v175
	v_rcp_f32_e32 v176, v176
	v_rcp_f32_e32 v177, v177
	v_pk_mul_f32 v[22:23], v[22:23], v[174:175]
	v_pk_mul_f32 v[24:25], v[24:25], v[176:177]
	v_pk_mul_f32 v[18:19], v[18:19], v[22:23]
	v_pk_mul_f32 v[20:21], v[20:21], v[24:25]
	v_cvt_pk_bf16_f32 v18, v18, v19
	v_cvt_pk_bf16_f32 v19, v20, v21
	global_store_short v210, v18, s[16:17]
	global_store_short_d16_hi v211, v18, s[16:17]
	global_store_short v212, v19, s[16:17]
	global_store_short_d16_hi v213, v19, s[16:17]
	v_pk_mul_f32 v[30:31], v[30:31], v[202:203]
	v_pk_mul_f32 v[32:33], v[32:33], v[204:205]
	v_pk_mul_f32 v[174:175], v[214:215], v[30:31]
	v_pk_mul_f32 v[176:177], v[214:215], v[32:33]
	v_exp_f32_e32 v174, v174
	v_exp_f32_e32 v175, v175
	v_exp_f32_e32 v176, v176
	v_exp_f32_e32 v177, v177
	v_pk_mul_f32 v[26:27], v[26:27], v[202:203]
	v_pk_mul_f32 v[28:29], v[28:29], v[204:205]
	v_pk_add_f32 v[174:175], v[216:217], v[174:175]
	v_pk_add_f32 v[176:177], v[216:217], v[176:177]
	v_rcp_f32_e32 v174, v174
	v_rcp_f32_e32 v175, v175
	v_rcp_f32_e32 v176, v176
	v_rcp_f32_e32 v177, v177
	v_pk_mul_f32 v[30:31], v[30:31], v[174:175]
	v_pk_mul_f32 v[32:33], v[32:33], v[176:177]
	v_pk_mul_f32 v[26:27], v[26:27], v[30:31]
	v_pk_mul_f32 v[28:29], v[28:29], v[32:33]
	v_cvt_pk_bf16_f32 v26, v26, v27
	v_cvt_pk_bf16_f32 v27, v28, v29
	global_store_short v210, v26, s[16:17] offset:128
	global_store_short_d16_hi v211, v26, s[16:17] offset:128
	global_store_short v212, v27, s[16:17] offset:128
	global_store_short_d16_hi v213, v27, s[16:17] offset:128
	s_add_u32 s16, s16, 0x16800
	s_addc_u32 s17, s17, 0
	v_pk_mul_f32 v[10:11], v[10:11], v[206:207]
	v_pk_mul_f32 v[12:13], v[12:13], v[208:209]
	v_pk_mul_f32 v[174:175], v[214:215], v[10:11]
	v_pk_mul_f32 v[176:177], v[214:215], v[12:13]
	v_exp_f32_e32 v174, v174
	v_exp_f32_e32 v175, v175
	v_exp_f32_e32 v176, v176
	v_exp_f32_e32 v177, v177
	v_pk_mul_f32 v[2:3], v[2:3], v[206:207]
	v_pk_mul_f32 v[4:5], v[4:5], v[208:209]
	v_pk_add_f32 v[174:175], v[216:217], v[174:175]
	v_pk_add_f32 v[176:177], v[216:217], v[176:177]
	v_rcp_f32_e32 v174, v174
	v_rcp_f32_e32 v175, v175
	v_rcp_f32_e32 v176, v176
	v_rcp_f32_e32 v177, v177
	v_pk_mul_f32 v[10:11], v[10:11], v[174:175]
	v_pk_mul_f32 v[12:13], v[12:13], v[176:177]
	v_pk_mul_f32 v[2:3], v[2:3], v[10:11]
	v_pk_mul_f32 v[4:5], v[4:5], v[12:13]
	v_cvt_pk_bf16_f32 v2, v2, v3
	v_cvt_pk_bf16_f32 v3, v4, v5
	global_store_short v210, v2, s[16:17]
	global_store_short_d16_hi v211, v2, s[16:17]
	global_store_short v212, v3, s[16:17]
	global_store_short_d16_hi v213, v3, s[16:17]
	v_pk_mul_f32 v[14:15], v[14:15], v[206:207]
	v_pk_mul_f32 v[16:17], v[16:17], v[208:209]
	v_pk_mul_f32 v[174:175], v[214:215], v[14:15]
	v_pk_mul_f32 v[176:177], v[214:215], v[16:17]
	v_exp_f32_e32 v174, v174
	v_exp_f32_e32 v175, v175
	v_exp_f32_e32 v176, v176
	v_exp_f32_e32 v177, v177
	v_pk_mul_f32 v[6:7], v[6:7], v[206:207]
	v_pk_mul_f32 v[8:9], v[8:9], v[208:209]
	v_pk_add_f32 v[174:175], v[216:217], v[174:175]
	v_pk_add_f32 v[176:177], v[216:217], v[176:177]
	v_rcp_f32_e32 v174, v174
	v_rcp_f32_e32 v175, v175
	v_rcp_f32_e32 v176, v176
	v_rcp_f32_e32 v177, v177
	v_pk_mul_f32 v[14:15], v[14:15], v[174:175]
	v_pk_mul_f32 v[16:17], v[16:17], v[176:177]
	v_pk_mul_f32 v[6:7], v[6:7], v[14:15]
	v_pk_mul_f32 v[8:9], v[8:9], v[16:17]
	v_cvt_pk_bf16_f32 v6, v6, v7
	v_cvt_pk_bf16_f32 v7, v8, v9
	global_store_short v210, v6, s[16:17] offset:128
	global_store_short_d16_hi v211, v6, s[16:17] offset:128
	global_store_short v212, v7, s[16:17] offset:128
	global_store_short_d16_hi v213, v7, s[16:17] offset:128
	s_xor_b32 s37, s37, 1
	s_andn2_b64 vcc, exec, s[14:15]
	s_mov_b32 s41, s22
	s_cbranch_vccz .LBB0_95

; #define GAS __attribute__((address_space(1)))
; __device__ __forceinline__ unsigned pk2(float lo, float hi) { unsigned r; asm("s_nop 1\n\tv_cvt_pk_bf16_f32 %0, %1, %2" : "=v"(r) : "v"(lo), "v"(hi)); return r; }
; __device__ __forceinline__ unsigned f2bf(float f) { return pk2(f, f) & 0xffffu; }
; __device__ __forceinline__ float sigmoidf_(float v) { return __builtin_amdgcn_rcpf(1.f + __builtin_amdgcn_exp2f(-LOG2E * v)); }
; __device__ __forceinline__ void phase_up(int pass) {
;     ...
;     if (L < NT_) { tile_coords(L, nN, pm, pn); gemm_prefetch<DM>(A, Wgu, pm * 256, pn * 256); load_rr(ssq, pm * 256, par ^ 1); }
;     EPI_IDS
;     const float* rr = (const float*)(smem_raw + LDS_RR) + par * 256;
;     GAS char* tb = (GAS char*)act + ((size_t)brow * FFP + (bcol >> 1)) * 2;
;     const unsigned off0 = (unsigned)((wr * 64 + fq * 4) * FFP + wc * 16 + fr) * 2u;
; #pragma unroll
;     for (int ai = 0; ai < 2; ++ai)
; #pragma unroll
;       for (int m = 0; m < 4; ++m)
; #pragma unroll
;         for (int j = 0; j < 4; ++j) {
;           const int rowl = ai * 128 + wr * 64 + m * 16 + fq * 4 + j;
;           const float r = rr[rowl];
; #pragma unroll
;           for (int bj = 0; bj < 2; ++bj) {
;             const float g = acc[ai][bj][m][0][j] * r, u = acc[ai][bj][m][1][j] * r;
;             const float v = g * sigmoidf_(g) * u;
;             *(GAS unsigned short*)(tb + (off0 + (unsigned)(((ai * 128 + m * 16 + j) * FFP + bj * 64) * 2))) = (unsigned short)f2bf(v);
;           }
;         }
;     par ^= 1;
.LBB0_880:
	v_ashrrev_i32_e32 v218, 2, v170
	v_and_b32_e32 v218, 0xffffffc0, v218
	v_lshrrev_b32_e32 v174, 2, v170
	v_and_b32_e32 v175, 12, v174
	v_or_b32_e32 v176, v218, v175
	v_and_b32_e32 v174, 48, v174
	v_and_b32_e32 v177, 15, v170
	v_mul_u32_u24_e32 v210, 0xb40, v176
	v_add3_u32 v210, v210, v174, v177
	v_lshlrev_b32_e32 v210, 1, v210
	v_add_u32_e32 v211, 0x1680, v210
	v_add_u32_e32 v212, 0x2d00, v210
	v_add_u32_e32 v213, 0x4380, v210
	s_lshl_b32 s16, s37, 10
	s_add_i32 s16, s16, 0x20100
	v_lshl_add_u32 v218, v176, 2, s16
	ds_read_b128 v[178:181], v218
	ds_read_b128 v[182:185], v218 offset:64
	ds_read_b128 v[186:189], v218 offset:128
	ds_read_b128 v[190:193], v218 offset:192
	ds_read_b128 v[194:197], v218 offset:512
	ds_read_b128 v[198:201], v218 offset:576
	ds_read_b128 v[202:205], v218 offset:640
	ds_read_b128 v[206:209], v218 offset:704
	v_mov_b32_e32 v214, 0xbfb8aa3b
	v_mov_b32_e32 v215, 0xbfb8aa3b
	v_mov_b32_e32 v216, 1.0
	v_mov_b32_e32 v217, 1.0
	s_lshl_b32 s17, s41, 7
	s_mul_hi_i32 s15, s14, 0xb40
	s_mulk_i32 s14, 0xb40
	s_ashr_i32 s18, s17, 31
	s_add_u32 s14, s14, s17
	s_addc_u32 s15, s15, s18
	s_lshl_b64 s[14:15], s[14:15], 1
	s_add_u32 s14, s35, s14
	s_addc_u32 s15, s36, s15
	s_waitcnt lgkmcnt(0)
	v_pk_mul_f32 v[118:119], v[118:119], v[178:179]
	v_pk_mul_f32 v[120:121], v[120:121], v[180:181]
	v_pk_mul_f32 v[174:175], v[214:215], v[118:119]
	v_pk_mul_f32 v[176:177], v[214:215], v[120:121]
	v_exp_f32_e32 v174, v174
	v_exp_f32_e32 v175, v175
	v_exp_f32_e32 v176, v176
	v_exp_f32_e32 v177, v177
	v_pk_mul_f32 v[114:115], v[114:115], v[178:179]
	v_pk_mul_f32 v[116:117], v[116:117], v[180:181]
	v_pk_add_f32 v[174:175], v[216:217], v[174:175]
	v_pk_add_f32 v[176:177], v[216:217], v[176:177]
	v_rcp_f32_e32 v174, v174
	v_rcp_f32_e32 v175, v175
	v_rcp_f32_e32 v176, v176
	v_rcp_f32_e32 v177, v177
	v_pk_mul_f32 v[118:119], v[118:119], v[174:175]
	v_pk_mul_f32 v[120:121], v[120:121], v[176:177]
	v_pk_mul_f32 v[114:115], v[114:115], v[118:119]
	v_pk_mul_f32 v[116:117], v[116:117], v[120:121]
	v_cvt_pk_bf16_f32 v114, v114, v115
	v_cvt_pk_bf16_f32 v115, v116, v117
	global_store_short v210, v114, s[14:15]
	global_store_short_d16_hi v211, v114, s[14:15]
	global_store_short v212, v115, s[14:15]
	global_store_short_d16_hi v213, v115, s[14:15]
	v_pk_mul_f32 v[126:127], v[126:127], v[178:179]
	v_pk_mul_f32 v[128:129], v[128:129], v[180:181]
	v_pk_mul_f32 v[174:175], v[214:215], v[126:127]
	v_pk_mul_f32 v[176:177], v[214:215], v[128:129]
	v_exp_f32_e32 v174, v174
	v_exp_f32_e32 v175, v175
	v_exp_f32_e32 v176, v176
	v_exp_f32_e32 v177, v177
	v_pk_mul_f32 v[122:123], v[122:123], v[178:179]
	v_pk_mul_f32 v[124:125], v[124:125], v[180:181]
	v_pk_add_f32 v[174:175], v[216:217], v[174:175]
	v_pk_add_f32 v[176:177], v[216:217], v[176:177]
	v_rcp_f32_e32 v174, v174
	v_rcp_f32_e32 v175, v175
	v_rcp_f32_e32 v176, v176
	v_rcp_f32_e32 v177, v177
	v_pk_mul_f32 v[126:127], v[126:127], v[174:175]
	v_pk_mul_f32 v[128:129], v[128:129], v[176:177]
	v_pk_mul_f32 v[122:123], v[122:123], v[126:127]
	v_pk_mul_f32 v[124:125], v[124:125], v[128:129]
	v_cvt_pk_bf16_f32 v122, v122, v123
	v_cvt_pk_bf16_f32 v123, v124, v125
	global_store_short v210, v122, s[14:15] offset:128
	global_store_short_d16_hi v211, v122, s[14:15] offset:128
	global_store_short v212, v123, s[14:15] offset:128
	global_store_short_d16_hi v213, v123, s[14:15] offset:128
	s_add_u32 s14, s14, 0x16800
	s_addc_u32 s15, s15, 0
	v_pk_mul_f32 v[102:103], v[102:103], v[182:183]
	v_pk_mul_f32 v[104:105], v[104:105], v[184:185]
	v_pk_mul_f32 v[174:175], v[214:215], v[102:103]
	v_pk_mul_f32 v[176:177], v[214:215], v[104:105]
	v_exp_f32_e32 v174, v174
	v_exp_f32_e32 v175, v175
	v_exp_f32_e32 v176, v176
	v_exp_f32_e32 v177, v177
	v_pk_mul_f32 v[98:99], v[98:99], v[182:183]
	v_pk_mul_f32 v[100:101], v[100:101], v[184:185]
	v_pk_add_f32 v[174:175], v[216:217], v[174:175]
	v_pk_add_f32 v[176:177], v[216:217], v[176:177]
	v_rcp_f32_e32 v174, v174
	v_rcp_f32_e32 v175, v175
	v_rcp_f32_e32 v176, v176
	v_rcp_f32_e32 v177, v177
	v_pk_mul_f32 v[102:103], v[102:103], v[174:175]
	v_pk_mul_f32 v[104:105], v[104:105], v[176:177]
	v_pk_mul_f32 v[98:99], v[98:99], v[102:103]
	v_pk_mul_f32 v[100:101], v[100:101], v[104:105]
	v_cvt_pk_bf16_f32 v98, v98, v99
	v_cvt_pk_bf16_f32 v99, v100, v101
	global_store_short v210, v98, s[14:15]
	global_store_short_d16_hi v211, v98, s[14:15]
	global_store_short v212, v99, s[14:15]
	global_store_short_d16_hi v213, v99, s[14:15]
	v_pk_mul_f32 v[110:111], v[110:111], v[182:183]
	v_pk_mul_f32 v[112:113], v[112:113], v[184:185]
	v_pk_mul_f32 v[174:175], v[214:215], v[110:111]
	v_pk_mul_f32 v[176:177], v[214:215], v[112:113]
	v_exp_f32_e32 v174, v174
	v_exp_f32_e32 v175, v175
	v_exp_f32_e32 v176, v176
	v_exp_f32_e32 v177, v177
	v_pk_mul_f32 v[106:107], v[106:107], v[182:183]
	v_pk_mul_f32 v[108:109], v[108:109], v[184:185]
	v_pk_add_f32 v[174:175], v[216:217], v[174:175]
	v_pk_add_f32 v[176:177], v[216:217], v[176:177]
	v_rcp_f32_e32 v174, v174
	v_rcp_f32_e32 v175, v175
	v_rcp_f32_e32 v176, v176
	v_rcp_f32_e32 v177, v177
	v_pk_mul_f32 v[110:111], v[110:111], v[174:175]
	v_pk_mul_f32 v[112:113], v[112:113], v[176:177]
	v_pk_mul_f32 v[106:107], v[106:107], v[110:111]
	v_pk_mul_f32 v[108:109], v[108:109], v[112:113]
	v_cvt_pk_bf16_f32 v106, v106, v107
	v_cvt_pk_bf16_f32 v107, v108, v109
	global_store_short v210, v106, s[14:15] offset:128
	global_store_short_d16_hi v211, v106, s[14:15] offset:128
	global_store_short v212, v107, s[14:15] offset:128
	global_store_short_d16_hi v213, v107, s[14:15] offset:128
	s_add_u32 s14, s14, 0x16800
	s_addc_u32 s15, s15, 0
	v_pk_mul_f32 v[86:87], v[86:87], v[186:187]
; #define GAS __attribute__((address_space(1)))
; __device__ __forceinline__ unsigned pk2(float lo, float hi) { unsigned r; asm("s_nop 1\n\tv_cvt_pk_bf16_f32 %0, %1, %2" : "=v"(r) : "v"(lo), "v"(hi)); return r; }
; __device__ __forceinline__ unsigned f2bf(float f) { return pk2(f, f) & 0xffffu; }
; __device__ __forceinline__ float sigmoidf_(float v) { return __builtin_amdgcn_rcpf(1.f + __builtin_amdgcn_exp2f(-LOG2E * v)); }
; __device__ __forceinline__ void phase_up(int pass) {
;     ...
;     if (L < NT_) { tile_coords(L, nN, pm, pn); gemm_prefetch<DM>(A, Wgu, pm * 256, pn * 256); load_rr(ssq, pm * 256, par ^ 1); }
;     EPI_IDS
;     const float* rr = (const float*)(smem_raw + LDS_RR) + par * 256;
;     GAS char* tb = (GAS char*)act + ((size_t)brow * FFP + (bcol >> 1)) * 2;
;     const unsigned off0 = (unsigned)((wr * 64 + fq * 4) * FFP + wc * 16 + fr) * 2u;
; #pragma unroll
;     for (int ai = 0; ai < 2; ++ai)
; #pragma unroll
;       for (int m = 0; m < 4; ++m)
; #pragma unroll
;         for (int j = 0; j < 4; ++j) {
;           const int rowl = ai * 128 + wr * 64 + m * 16 + fq * 4 + j;
;           const float r = rr[rowl];
; #pragma unroll
;           for (int bj = 0; bj < 2; ++bj) {
;             const float g = acc[ai][bj][m][0][j] * r, u = acc[ai][bj][m][1][j] * r;
;             const float v = g * sigmoidf_(g) * u;
;             *(GAS unsigned short*)(tb + (off0 + (unsigned)(((ai * 128 + m * 16 + j) * FFP + bj * 64) * 2))) = (unsigned short)f2bf(v);
;           }
;         }
;     par ^= 1;
	v_pk_mul_f32 v[88:89], v[88:89], v[188:189]
	v_pk_mul_f32 v[174:175], v[214:215], v[86:87]
	v_pk_mul_f32 v[176:177], v[214:215], v[88:89]
	v_exp_f32_e32 v174, v174
	v_exp_f32_e32 v175, v175
	v_exp_f32_e32 v176, v176
	v_exp_f32_e32 v177, v177
	v_pk_mul_f32 v[82:83], v[82:83], v[186:187]
	v_pk_mul_f32 v[84:85], v[84:85], v[188:189]
	v_pk_add_f32 v[174:175], v[216:217], v[174:175]
	v_pk_add_f32 v[176:177], v[216:217], v[176:177]
	v_rcp_f32_e32 v174, v174
	v_rcp_f32_e32 v175, v175
	v_rcp_f32_e32 v176, v176
	v_rcp_f32_e32 v177, v177
	v_pk_mul_f32 v[86:87], v[86:87], v[174:175]
	v_pk_mul_f32 v[88:89], v[88:89], v[176:177]
	v_pk_mul_f32 v[82:83], v[82:83], v[86:87]
	v_pk_mul_f32 v[84:85], v[84:85], v[88:89]
	v_cvt_pk_bf16_f32 v82, v82, v83
	v_cvt_pk_bf16_f32 v83, v84, v85
	global_store_short v210, v82, s[14:15]
	global_store_short_d16_hi v211, v82, s[14:15]
	global_store_short v212, v83, s[14:15]
	global_store_short_d16_hi v213, v83, s[14:15]
	v_pk_mul_f32 v[94:95], v[94:95], v[186:187]
	v_pk_mul_f32 v[96:97], v[96:97], v[188:189]
	v_pk_mul_f32 v[174:175], v[214:215], v[94:95]
	v_pk_mul_f32 v[176:177], v[214:215], v[96:97]
	v_exp_f32_e32 v174, v174
	v_exp_f32_e32 v175, v175
	v_exp_f32_e32 v176, v176
	v_exp_f32_e32 v177, v177
	v_pk_mul_f32 v[90:91], v[90:91], v[186:187]
	v_pk_mul_f32 v[92:93], v[92:93], v[188:189]
	v_pk_add_f32 v[174:175], v[216:217], v[174:175]
	v_pk_add_f32 v[176:177], v[216:217], v[176:177]
	v_rcp_f32_e32 v174, v174
	v_rcp_f32_e32 v175, v175
	v_rcp_f32_e32 v176, v176
	v_rcp_f32_e32 v177, v177
	v_pk_mul_f32 v[94:95], v[94:95], v[174:175]
	v_pk_mul_f32 v[96:97], v[96:97], v[176:177]
	v_pk_mul_f32 v[90:91], v[90:91], v[94:95]
	v_pk_mul_f32 v[92:93], v[92:93], v[96:97]
	v_cvt_pk_bf16_f32 v90, v90, v91
	v_cvt_pk_bf16_f32 v91, v92, v93
	global_store_short v210, v90, s[14:15] offset:128
	global_store_short_d16_hi v211, v90, s[14:15] offset:128
	global_store_short v212, v91, s[14:15] offset:128
	global_store_short_d16_hi v213, v91, s[14:15] offset:128
	s_add_u32 s14, s14, 0x16800
	s_addc_u32 s15, s15, 0
	v_pk_mul_f32 v[70:71], v[70:71], v[190:191]
	v_pk_mul_f32 v[72:73], v[72:73], v[192:193]
	v_pk_mul_f32 v[174:175], v[214:215], v[70:71]
	v_pk_mul_f32 v[176:177], v[214:215], v[72:73]
	v_exp_f32_e32 v174, v174
	v_exp_f32_e32 v175, v175
	v_exp_f32_e32 v176, v176
	v_exp_f32_e32 v177, v177
	v_pk_mul_f32 v[66:67], v[66:67], v[190:191]
	v_pk_mul_f32 v[68:69], v[68:69], v[192:193]
	v_pk_add_f32 v[174:175], v[216:217], v[174:175]
	v_pk_add_f32 v[176:177], v[216:217], v[176:177]
	v_rcp_f32_e32 v174, v174
	v_rcp_f32_e32 v175, v175
	v_rcp_f32_e32 v176, v176
	v_rcp_f32_e32 v177, v177
	v_pk_mul_f32 v[70:71], v[70:71], v[174:175]
	v_pk_mul_f32 v[72:73], v[72:73], v[176:177]
	v_pk_mul_f32 v[66:67], v[66:67], v[70:71]
	v_pk_mul_f32 v[68:69], v[68:69], v[72:73]
	v_cvt_pk_bf16_f32 v66, v66, v67
	v_cvt_pk_bf16_f32 v67, v68, v69
	global_store_short v210, v66, s[14:15]
	global_store_short_d16_hi v211, v66, s[14:15]
	global_store_short v212, v67, s[14:15]
	global_store_short_d16_hi v213, v67, s[14:15]
	v_pk_mul_f32 v[78:79], v[78:79], v[190:191]
	v_pk_mul_f32 v[80:81], v[80:81], v[192:193]
	v_pk_mul_f32 v[174:175], v[214:215], v[78:79]
	v_pk_mul_f32 v[176:177], v[214:215], v[80:81]
	v_exp_f32_e32 v174, v174
	v_exp_f32_e32 v175, v175
	v_exp_f32_e32 v176, v176
	v_exp_f32_e32 v177, v177
	v_pk_mul_f32 v[74:75], v[74:75], v[190:191]
	v_pk_mul_f32 v[76:77], v[76:77], v[192:193]
	v_pk_add_f32 v[174:175], v[216:217], v[174:175]
	v_pk_add_f32 v[176:177], v[216:217], v[176:177]
	v_rcp_f32_e32 v174, v174
	v_rcp_f32_e32 v175, v175
	v_rcp_f32_e32 v176, v176
	v_rcp_f32_e32 v177, v177
	v_pk_mul_f32 v[78:79], v[78:79], v[174:175]
	v_pk_mul_f32 v[80:81], v[80:81], v[176:177]
	v_pk_mul_f32 v[74:75], v[74:75], v[78:79]
	v_pk_mul_f32 v[76:77], v[76:77], v[80:81]
	v_cvt_pk_bf16_f32 v74, v74, v75
	v_cvt_pk_bf16_f32 v75, v76, v77
	global_store_short v210, v74, s[14:15] offset:128
	global_store_short_d16_hi v211, v74, s[14:15] offset:128
	global_store_short v212, v75, s[14:15] offset:128
	global_store_short_d16_hi v213, v75, s[14:15] offset:128
	s_add_u32 s14, s14, 0x70800
	s_addc_u32 s15, s15, 0
	v_pk_mul_f32 v[54:55], v[54:55], v[194:195]
	v_pk_mul_f32 v[56:57], v[56:57], v[196:197]
	v_pk_mul_f32 v[174:175], v[214:215], v[54:55]
	v_pk_mul_f32 v[176:177], v[214:215], v[56:57]
	v_exp_f32_e32 v174, v174
	v_exp_f32_e32 v175, v175
	v_exp_f32_e32 v176, v176
	v_exp_f32_e32 v177, v177
	v_pk_mul_f32 v[50:51], v[50:51], v[194:195]
	v_pk_mul_f32 v[52:53], v[52:53], v[196:197]
	v_pk_add_f32 v[174:175], v[216:217], v[174:175]
	v_pk_add_f32 v[176:177], v[216:217], v[176:177]
	v_rcp_f32_e32 v174, v174
	v_rcp_f32_e32 v175, v175
	v_rcp_f32_e32 v176, v176
	v_rcp_f32_e32 v177, v177
	v_pk_mul_f32 v[54:55], v[54:55], v[174:175]
	v_pk_mul_f32 v[56:57], v[56:57], v[176:177]
	v_pk_mul_f32 v[50:51], v[50:51], v[54:55]
	v_pk_mul_f32 v[52:53], v[52:53], v[56:57]
	v_cvt_pk_bf16_f32 v50, v50, v51
	v_cvt_pk_bf16_f32 v51, v52, v53
	global_store_short v210, v50, s[14:15]
	global_store_short_d16_hi v211, v50, s[14:15]
	global_store_short v212, v51, s[14:15]
	global_store_short_d16_hi v213, v51, s[14:15]
	v_pk_mul_f32 v[62:63], v[62:63], v[194:195]
	v_pk_mul_f32 v[64:65], v[64:65], v[196:197]
	v_pk_mul_f32 v[174:175], v[214:215], v[62:63]
	v_pk_mul_f32 v[176:177], v[214:215], v[64:65]
	v_exp_f32_e32 v174, v174
	v_exp_f32_e32 v175, v175
	v_exp_f32_e32 v176, v176
	v_exp_f32_e32 v177, v177
	v_pk_mul_f32 v[58:59], v[58:59], v[194:195]
	v_pk_mul_f32 v[60:61], v[60:61], v[196:197]
	v_pk_add_f32 v[174:175], v[216:217], v[174:175]
	v_pk_add_f32 v[176:177], v[216:217], v[176:177]
	v_rcp_f32_e32 v174, v174
; #define GAS __attribute__((address_space(1)))
; __device__ __forceinline__ unsigned pk2(float lo, float hi) { unsigned r; asm("s_nop 1\n\tv_cvt_pk_bf16_f32 %0, %1, %2" : "=v"(r) : "v"(lo), "v"(hi)); return r; }
; __device__ __forceinline__ unsigned f2bf(float f) { return pk2(f, f) & 0xffffu; }
; __device__ __forceinline__ float sigmoidf_(float v) { return __builtin_amdgcn_rcpf(1.f + __builtin_amdgcn_exp2f(-LOG2E * v)); }
; __device__ __forceinline__ void phase_up(int pass) {
;     ...
;     if (L < NT_) { tile_coords(L, nN, pm, pn); gemm_prefetch<DM>(A, Wgu, pm * 256, pn * 256); load_rr(ssq, pm * 256, par ^ 1); }
;     EPI_IDS
;     const float* rr = (const float*)(smem_raw + LDS_RR) + par * 256;
;     GAS char* tb = (GAS char*)act + ((size_t)brow * FFP + (bcol >> 1)) * 2;
;     const unsigned off0 = (unsigned)((wr * 64 + fq * 4) * FFP + wc * 16 + fr) * 2u;
; #pragma unroll
;     for (int ai = 0; ai < 2; ++ai)
; #pragma unroll
;       for (int m = 0; m < 4; ++m)
; #pragma unroll
;         for (int j = 0; j < 4; ++j) {
;           const int rowl = ai * 128 + wr * 64 + m * 16 + fq * 4 + j;
;           const float r = rr[rowl];
; #pragma unroll
;           for (int bj = 0; bj < 2; ++bj) {
;             const float g = acc[ai][bj][m][0][j] * r, u = acc[ai][bj][m][1][j] * r;
;             const float v = g * sigmoidf_(g) * u;
;             *(GAS unsigned short*)(tb + (off0 + (unsigned)(((ai * 128 + m * 16 + j) * FFP + bj * 64) * 2))) = (unsigned short)f2bf(v);
;           }
;         }
;     par ^= 1;
	v_rcp_f32_e32 v175, v175
	v_rcp_f32_e32 v176, v176
	v_rcp_f32_e32 v177, v177
	v_pk_mul_f32 v[62:63], v[62:63], v[174:175]
	v_pk_mul_f32 v[64:65], v[64:65], v[176:177]
	v_pk_mul_f32 v[58:59], v[58:59], v[62:63]
	v_pk_mul_f32 v[60:61], v[60:61], v[64:65]
	v_cvt_pk_bf16_f32 v58, v58, v59
	v_cvt_pk_bf16_f32 v59, v60, v61
	global_store_short v210, v58, s[14:15] offset:128
	global_store_short_d16_hi v211, v58, s[14:15] offset:128
	global_store_short v212, v59, s[14:15] offset:128
	global_store_short_d16_hi v213, v59, s[14:15] offset:128
	s_add_u32 s14, s14, 0x16800
	s_addc_u32 s15, s15, 0
	v_pk_mul_f32 v[42:43], v[42:43], v[198:199]
	v_pk_mul_f32 v[44:45], v[44:45], v[200:201]
	v_pk_mul_f32 v[174:175], v[214:215], v[42:43]
	v_pk_mul_f32 v[176:177], v[214:215], v[44:45]
	v_exp_f32_e32 v174, v174
	v_exp_f32_e32 v175, v175
	v_exp_f32_e32 v176, v176
	v_exp_f32_e32 v177, v177
	v_pk_mul_f32 v[34:35], v[34:35], v[198:199]
	v_pk_mul_f32 v[36:37], v[36:37], v[200:201]
	v_pk_add_f32 v[174:175], v[216:217], v[174:175]
	v_pk_add_f32 v[176:177], v[216:217], v[176:177]
	v_rcp_f32_e32 v174, v174
	v_rcp_f32_e32 v175, v175
	v_rcp_f32_e32 v176, v176
	v_rcp_f32_e32 v177, v177
	v_pk_mul_f32 v[42:43], v[42:43], v[174:175]
	v_pk_mul_f32 v[44:45], v[44:45], v[176:177]
	v_pk_mul_f32 v[34:35], v[34:35], v[42:43]
	v_pk_mul_f32 v[36:37], v[36:37], v[44:45]
	v_cvt_pk_bf16_f32 v34, v34, v35
	v_cvt_pk_bf16_f32 v35, v36, v37
	global_store_short v210, v34, s[14:15]
	global_store_short_d16_hi v211, v34, s[14:15]
	global_store_short v212, v35, s[14:15]
	global_store_short_d16_hi v213, v35, s[14:15]
	v_pk_mul_f32 v[46:47], v[46:47], v[198:199]
	v_pk_mul_f32 v[48:49], v[48:49], v[200:201]
	v_pk_mul_f32 v[174:175], v[214:215], v[46:47]
	v_pk_mul_f32 v[176:177], v[214:215], v[48:49]
	v_exp_f32_e32 v174, v174
	v_exp_f32_e32 v175, v175
	v_exp_f32_e32 v176, v176
	v_exp_f32_e32 v177, v177
	v_pk_mul_f32 v[38:39], v[38:39], v[198:199]
	v_pk_mul_f32 v[40:41], v[40:41], v[200:201]
	v_pk_add_f32 v[174:175], v[216:217], v[174:175]
	v_pk_add_f32 v[176:177], v[216:217], v[176:177]
	v_rcp_f32_e32 v174, v174
	v_rcp_f32_e32 v175, v175
	v_rcp_f32_e32 v176, v176
	v_rcp_f32_e32 v177, v177
	v_pk_mul_f32 v[46:47], v[46:47], v[174:175]
	v_pk_mul_f32 v[48:49], v[48:49], v[176:177]
	v_pk_mul_f32 v[38:39], v[38:39], v[46:47]
	v_pk_mul_f32 v[40:41], v[40:41], v[48:49]
	v_cvt_pk_bf16_f32 v38, v38, v39
	v_cvt_pk_bf16_f32 v39, v40, v41
	global_store_short v210, v38, s[14:15] offset:128
	global_store_short_d16_hi v211, v38, s[14:15] offset:128
	global_store_short v212, v39, s[14:15] offset:128
	global_store_short_d16_hi v213, v39, s[14:15] offset:128
	s_add_u32 s14, s14, 0x16800
	s_addc_u32 s15, s15, 0
	v_pk_mul_f32 v[22:23], v[22:23], v[202:203]
	v_pk_mul_f32 v[24:25], v[24:25], v[204:205]
	v_pk_mul_f32 v[174:175], v[214:215], v[22:23]
	v_pk_mul_f32 v[176:177], v[214:215], v[24:25]
	v_exp_f32_e32 v174, v174
	v_exp_f32_e32 v175, v175
	v_exp_f32_e32 v176, v176
	v_exp_f32_e32 v177, v177
	v_pk_mul_f32 v[18:19], v[18:19], v[202:203]
	v_pk_mul_f32 v[20:21], v[20:21], v[204:205]
	v_pk_add_f32 v[174:175], v[216:217], v[174:175]
	v_pk_add_f32 v[176:177], v[216:217], v[176:177]
	v_rcp_f32_e32 v174, v174
	v_rcp_f32_e32 v175, v175
	v_rcp_f32_e32 v176, v176
	v_rcp_f32_e32 v177, v177
	v_pk_mul_f32 v[22:23], v[22:23], v[174:175]
	v_pk_mul_f32 v[24:25], v[24:25], v[176:177]
	v_pk_mul_f32 v[18:19], v[18:19], v[22:23]
	v_pk_mul_f32 v[20:21], v[20:21], v[24:25]
	v_cvt_pk_bf16_f32 v18, v18, v19
	v_cvt_pk_bf16_f32 v19, v20, v21
	global_store_short v210, v18, s[14:15]
	global_store_short_d16_hi v211, v18, s[14:15]
	global_store_short v212, v19, s[14:15]
	global_store_short_d16_hi v213, v19, s[14:15]
	v_pk_mul_f32 v[30:31], v[30:31], v[202:203]
	v_pk_mul_f32 v[32:33], v[32:33], v[204:205]
	v_pk_mul_f32 v[174:175], v[214:215], v[30:31]
	v_pk_mul_f32 v[176:177], v[214:215], v[32:33]
	v_exp_f32_e32 v174, v174
	v_exp_f32_e32 v175, v175
	v_exp_f32_e32 v176, v176
	v_exp_f32_e32 v177, v177
	v_pk_mul_f32 v[26:27], v[26:27], v[202:203]
	v_pk_mul_f32 v[28:29], v[28:29], v[204:205]
	v_pk_add_f32 v[174:175], v[216:217], v[174:175]
	v_pk_add_f32 v[176:177], v[216:217], v[176:177]
	v_rcp_f32_e32 v174, v174
	v_rcp_f32_e32 v175, v175
	v_rcp_f32_e32 v176, v176
	v_rcp_f32_e32 v177, v177
	v_pk_mul_f32 v[30:31], v[30:31], v[174:175]
	v_pk_mul_f32 v[32:33], v[32:33], v[176:177]
	v_pk_mul_f32 v[26:27], v[26:27], v[30:31]
	v_pk_mul_f32 v[28:29], v[28:29], v[32:33]
	v_cvt_pk_bf16_f32 v26, v26, v27
	v_cvt_pk_bf16_f32 v27, v28, v29
	global_store_short v210, v26, s[14:15] offset:128
	global_store_short_d16_hi v211, v26, s[14:15] offset:128
	global_store_short v212, v27, s[14:15] offset:128
	global_store_short_d16_hi v213, v27, s[14:15] offset:128
	s_add_u32 s14, s14, 0x16800
	s_addc_u32 s15, s15, 0
	v_pk_mul_f32 v[10:11], v[10:11], v[206:207]
	v_pk_mul_f32 v[12:13], v[12:13], v[208:209]
	v_pk_mul_f32 v[174:175], v[214:215], v[10:11]
	v_pk_mul_f32 v[176:177], v[214:215], v[12:13]
	v_exp_f32_e32 v174, v174
	v_exp_f32_e32 v175, v175
	v_exp_f32_e32 v176, v176
	v_exp_f32_e32 v177, v177
	v_pk_mul_f32 v[2:3], v[2:3], v[206:207]
	v_pk_mul_f32 v[4:5], v[4:5], v[208:209]
	v_pk_add_f32 v[174:175], v[216:217], v[174:175]
	v_pk_add_f32 v[176:177], v[216:217], v[176:177]
	v_rcp_f32_e32 v174, v174
	v_rcp_f32_e32 v175, v175
	v_rcp_f32_e32 v176, v176
	v_rcp_f32_e32 v177, v177
	v_pk_mul_f32 v[10:11], v[10:11], v[174:175]
	v_pk_mul_f32 v[12:13], v[12:13], v[176:177]
	v_pk_mul_f32 v[2:3], v[2:3], v[10:11]
	v_pk_mul_f32 v[4:5], v[4:5], v[12:13]
	v_cvt_pk_bf16_f32 v2, v2, v3
	v_cvt_pk_bf16_f32 v3, v4, v5
	global_store_short v210, v2, s[14:15]
	global_store_short_d16_hi v211, v2, s[14:15]
	global_store_short v212, v3, s[14:15]
	global_store_short_d16_hi v213, v3, s[14:15]
	v_pk_mul_f32 v[14:15], v[14:15], v[206:207]
	v_pk_mul_f32 v[16:17], v[16:17], v[208:209]
	v_pk_mul_f32 v[174:175], v[214:215], v[14:15]
	v_pk_mul_f32 v[176:177], v[214:215], v[16:17]
	v_exp_f32_e32 v174, v174
	v_exp_f32_e32 v175, v175
	v_exp_f32_e32 v176, v176
	v_exp_f32_e32 v177, v177
	v_pk_mul_f32 v[6:7], v[6:7], v[206:207]
	v_pk_mul_f32 v[8:9], v[8:9], v[208:209]
	v_pk_add_f32 v[174:175], v[216:217], v[174:175]
	v_pk_add_f32 v[176:177], v[216:217], v[176:177]
	v_rcp_f32_e32 v174, v174
	v_rcp_f32_e32 v175, v175
	v_rcp_f32_e32 v176, v176
	v_rcp_f32_e32 v177, v177
	v_pk_mul_f32 v[14:15], v[14:15], v[174:175]
	v_pk_mul_f32 v[16:17], v[16:17], v[176:177]
	v_pk_mul_f32 v[6:7], v[6:7], v[14:15]
	v_pk_mul_f32 v[8:9], v[8:9], v[16:17]
	v_cvt_pk_bf16_f32 v6, v6, v7
	v_cvt_pk_bf16_f32 v7, v8, v9
	global_store_short v210, v6, s[14:15] offset:128
	global_store_short_d16_hi v211, v6, s[14:15] offset:128
	global_store_short v212, v7, s[14:15] offset:128
	global_store_short_d16_hi v213, v7, s[14:15] offset:128
	s_xor_b32 s37, s37, 1
	s_andn2_b64 vcc, exec, s[12:13]
	s_mov_b32 s41, s20
	s_cbranch_vccz .LBB0_890
